# v8 + K-loop: post-barrier waitcnt removed, all per-segment s_setprio removed, one static s_setprio 1 for waves 4-7 around the loop
# baseline (speedup 1.0000x reference)
.LBB0_344:
	s_add_i32 s4, s2, 2
	s_add_u32 s5, s68, s0
	s_addc_u32 s3, s69, s1
	s_add_u32 s33, s86, s0
	s_addc_u32 s35, s87, s1
	s_add_i32 s47, 0, 0x10000
	s_cmp_eq_u32 s21, s2
	s_cselect_b32 s3, s65, s3
	s_cselect_b32 s2, s64, s5
	v_add_u32_e32 v17, s47, v237
	s_cselect_b32 s57, s67, s35
	s_cselect_b32 s56, s66, s33
	s_add_i32 s5, 0, 0x14000
	ds_read_b128 v[134:137], v17
	ds_read_b128 v[138:141], v17 offset:1024
	ds_read_b128 v[142:145], v17 offset:2048
	ds_read_b128 v[146:149], v17 offset:3072
	v_add_u32_e32 v17, s5, v237
	ds_read_b128 v[150:153], v17
	ds_read_b128 v[154:157], v17 offset:1024
	ds_read_b128 v[158:161], v17 offset:2048
	ds_read_b128 v[162:165], v17 offset:3072
	v_lshl_add_u64 v[170:171], s[68:69], 0, v[132:133]
	s_add_i32 m0, s37, 0xc000
	ds_read_b128 v[166:169], v240
	ds_read_b128 v[186:189], v240 offset:1024
	ds_read_b128 v[190:193], v240 offset:2048
	ds_read_b128 v[194:197], v240 offset:3072
	ds_read_b128 v[198:201], v240 offset:4096
	ds_read_b128 v[202:205], v240 offset:5120
	ds_read_b128 v[206:209], v240 offset:6144
	ds_read_b128 v[210:213], v240 offset:7168
	global_load_lds_dwordx4 v[170:171], off
	v_lshl_add_u64 v[170:171], s[68:69], 0, v[18:19]
	s_add_i32 m0, s37, 0xe000
	s_nop 0
	global_load_lds_dwordx4 v[170:171], off
	s_waitcnt vmcnt(8)
	s_waitcnt lgkmcnt(0)
	s_barrier
	v_mfma_f32_16x16x32_bf16 v[8:11], v[134:137], v[166:169], v[8:11]
	v_mfma_f32_16x16x32_bf16 v[12:15], v[142:145], v[166:169], v[12:15]
	v_mfma_f32_16x16x32_bf16 v[28:31], v[134:137], v[190:193], v[28:31]
	v_mfma_f32_16x16x32_bf16 v[32:35], v[142:145], v[190:193], v[32:35]
	v_mfma_f32_16x16x32_bf16 v[36:39], v[134:137], v[198:201], v[36:39]
	v_mfma_f32_16x16x32_bf16 v[44:47], v[142:145], v[198:201], v[44:47]
	v_mfma_f32_16x16x32_bf16 v[80:83], v[134:137], v[206:209], v[80:83]
	v_mfma_f32_16x16x32_bf16 v[88:91], v[142:145], v[206:209], v[88:91]
	v_mfma_f32_16x16x32_bf16 v[8:11], v[138:141], v[186:189], v[8:11]
	v_mfma_f32_16x16x32_bf16 v[12:15], v[146:149], v[186:189], v[12:15]
	v_mfma_f32_16x16x32_bf16 v[28:31], v[138:141], v[194:197], v[28:31]
	v_mfma_f32_16x16x32_bf16 v[32:35], v[146:149], v[194:197], v[32:35]
	v_mfma_f32_16x16x32_bf16 v[36:39], v[138:141], v[202:205], v[36:39]
	v_mfma_f32_16x16x32_bf16 v[44:47], v[146:149], v[202:205], v[44:47]
	v_mfma_f32_16x16x32_bf16 v[80:83], v[138:141], v[210:213], v[80:83]
	v_mfma_f32_16x16x32_bf16 v[88:91], v[146:149], v[210:213], v[88:91]
	v_mfma_f32_16x16x32_bf16 v[0:3], v[150:153], v[166:169], v[0:3]
	v_mfma_f32_16x16x32_bf16 v[4:7], v[158:161], v[166:169], v[4:7]
	v_mfma_f32_16x16x32_bf16 v[20:23], v[150:153], v[190:193], v[20:23]
	v_mfma_f32_16x16x32_bf16 v[24:27], v[158:161], v[190:193], v[24:27]
	v_mfma_f32_16x16x32_bf16 v[40:43], v[150:153], v[198:201], v[40:43]
	v_mfma_f32_16x16x32_bf16 v[48:51], v[158:161], v[198:201], v[48:51]
	v_mfma_f32_16x16x32_bf16 v[60:63], v[150:153], v[206:209], v[60:63]
	v_mfma_f32_16x16x32_bf16 v[64:67], v[158:161], v[206:209], v[64:67]
	v_mfma_f32_16x16x32_bf16 v[0:3], v[154:157], v[186:189], v[0:3]
	v_mfma_f32_16x16x32_bf16 v[4:7], v[162:165], v[186:189], v[4:7]
	v_mfma_f32_16x16x32_bf16 v[20:23], v[154:157], v[194:197], v[20:23]
	v_mfma_f32_16x16x32_bf16 v[24:27], v[162:165], v[194:197], v[24:27]
	v_mfma_f32_16x16x32_bf16 v[40:43], v[154:157], v[202:205], v[40:43]
	v_mfma_f32_16x16x32_bf16 v[48:51], v[162:165], v[202:205], v[48:51]
	v_mfma_f32_16x16x32_bf16 v[60:63], v[154:157], v[210:213], v[60:63]
	v_mfma_f32_16x16x32_bf16 v[64:67], v[162:165], v[210:213], v[64:67]
	s_barrier
	s_add_i32 s33, s47, s17
	v_lshl_add_u64 v[170:171], s[56:57], 0, v[174:175]
	s_mov_b32 m0, s33
	ds_read_b128 v[166:169], v240 offset:16384
	ds_read_b128 v[186:189], v240 offset:17408
	ds_read_b128 v[190:193], v240 offset:18432
	ds_read_b128 v[194:197], v240 offset:19456
	ds_read_b128 v[198:201], v240 offset:20480
	ds_read_b128 v[202:205], v240 offset:21504
	ds_read_b128 v[206:209], v240 offset:22528
	ds_read_b128 v[210:213], v240 offset:23552
	global_load_lds_dwordx4 v[170:171], off
	s_add_i32 m0, s33, 0x2000
	v_lshl_add_u64 v[214:215], s[56:57], 0, v[178:179]
	s_add_u32 s56, s56, s36
	s_addc_u32 s57, s57, 0
	s_add_i32 s5, s5, s17
	global_load_lds_dwordx4 v[214:215], off
	v_lshl_add_u64 v[216:217], s[56:57], 0, v[174:175]
	s_mov_b32 m0, s5
	v_lshl_add_u64 v[224:225], s[56:57], 0, v[178:179]
	global_load_lds_dwordx4 v[216:217], off
	s_add_i32 m0, s5, 0x2000
	v_lshl_add_u64 v[226:227], s[2:3], 0, v[172:173]
	global_load_lds_dwordx4 v[224:225], off
	s_mov_b32 m0, s37
	v_lshl_add_u64 v[242:243], s[2:3], 0, v[176:177]
	global_load_lds_dwordx4 v[226:227], off
	s_mov_b32 m0, s45
	s_nop 0
	global_load_lds_dwordx4 v[242:243], off
	s_waitcnt vmcnt(8)
	s_waitcnt lgkmcnt(0)
	s_barrier
	v_mfma_f32_16x16x32_bf16 v[68:71], v[134:137], v[166:169], v[68:71]
	v_mfma_f32_16x16x32_bf16 v[72:75], v[142:145], v[166:169], v[72:75]
	v_mfma_f32_16x16x32_bf16 v[92:95], v[134:137], v[190:193], v[92:95]
	v_mfma_f32_16x16x32_bf16 v[96:99], v[142:145], v[190:193], v[96:99]
	v_mfma_f32_16x16x32_bf16 v[108:111], v[134:137], v[198:201], v[108:111]
	v_mfma_f32_16x16x32_bf16 v[112:115], v[142:145], v[198:201], v[112:115]
	v_mfma_f32_16x16x32_bf16 v[124:127], v[134:137], v[206:209], v[124:127]
	v_mfma_f32_16x16x32_bf16 v[128:131], v[142:145], v[206:209], v[128:131]
	v_mfma_f32_16x16x32_bf16 v[68:71], v[138:141], v[186:189], v[68:71]
	v_mfma_f32_16x16x32_bf16 v[72:75], v[146:149], v[186:189], v[72:75]
	v_mfma_f32_16x16x32_bf16 v[92:95], v[138:141], v[194:197], v[92:95]
	v_mfma_f32_16x16x32_bf16 v[96:99], v[146:149], v[194:197], v[96:99]
	v_mfma_f32_16x16x32_bf16 v[108:111], v[138:141], v[202:205], v[108:111]
	v_mfma_f32_16x16x32_bf16 v[112:115], v[146:149], v[202:205], v[112:115]
	v_mfma_f32_16x16x32_bf16 v[124:127], v[138:141], v[210:213], v[124:127]
	v_mfma_f32_16x16x32_bf16 v[128:131], v[146:149], v[210:213], v[128:131]
	v_mfma_f32_16x16x32_bf16 v[52:55], v[150:153], v[166:169], v[52:55]
	v_mfma_f32_16x16x32_bf16 v[56:59], v[158:161], v[166:169], v[56:59]
	v_mfma_f32_16x16x32_bf16 v[76:79], v[150:153], v[190:193], v[76:79]
	v_mfma_f32_16x16x32_bf16 v[84:87], v[158:161], v[190:193], v[84:87]
	v_mfma_f32_16x16x32_bf16 v[100:103], v[150:153], v[198:201], v[100:103]
	v_mfma_f32_16x16x32_bf16 v[104:107], v[158:161], v[198:201], v[104:107]
	v_mfma_f32_16x16x32_bf16 v[116:119], v[150:153], v[206:209], v[116:119]
	v_mfma_f32_16x16x32_bf16 v[120:123], v[158:161], v[206:209], v[120:123]
	v_mfma_f32_16x16x32_bf16 v[52:55], v[154:157], v[186:189], v[52:55]
	v_mfma_f32_16x16x32_bf16 v[56:59], v[162:165], v[186:189], v[56:59]
	v_mfma_f32_16x16x32_bf16 v[76:79], v[154:157], v[194:197], v[76:79]
	v_mfma_f32_16x16x32_bf16 v[84:87], v[162:165], v[194:197], v[84:87]
	v_mfma_f32_16x16x32_bf16 v[100:103], v[154:157], v[202:205], v[100:103]
	v_mfma_f32_16x16x32_bf16 v[104:107], v[162:165], v[202:205], v[104:107]
	v_mfma_f32_16x16x32_bf16 v[116:119], v[154:157], v[210:213], v[116:119]
	v_mfma_f32_16x16x32_bf16 v[120:123], v[162:165], v[210:213], v[120:123]
	s_barrier
	s_add_i32 s5, 0, 0x18000
	v_add_u32_e32 v17, s5, v237
	s_add_i32 s33, 0, 0x1c000
	ds_read_b128 v[134:137], v17
	ds_read_b128 v[138:141], v17 offset:1024
	ds_read_b128 v[142:145], v17 offset:2048
	ds_read_b128 v[146:149], v17 offset:3072
	v_add_u32_e32 v17, s33, v237
	ds_read_b128 v[150:153], v17
	ds_read_b128 v[154:157], v17 offset:1024
	ds_read_b128 v[158:161], v17 offset:2048
	ds_read_b128 v[162:165], v17 offset:3072
	s_add_u32 s2, s2, s36
	s_addc_u32 s3, s3, 0
	s_mov_b32 m0, s26
	v_lshl_add_u64 v[244:245], s[2:3], 0, v[172:173]
	ds_read_b128 v[166:169], v240 offset:32768
	ds_read_b128 v[186:189], v240 offset:33792
	ds_read_b128 v[190:193], v240 offset:34816
	ds_read_b128 v[194:197], v240 offset:35840
	ds_read_b128 v[198:201], v240 offset:36864
	ds_read_b128 v[202:205], v240 offset:37888
	ds_read_b128 v[206:209], v240 offset:38912
	ds_read_b128 v[210:213], v240 offset:39936
	global_load_lds_dwordx4 v[244:245], off
	v_lshl_add_u64 v[244:245], s[2:3], 0, v[176:177]
	s_mov_b32 m0, s27
	s_nop 0
	global_load_lds_dwordx4 v[244:245], off
	s_waitcnt vmcnt(8)
	s_waitcnt lgkmcnt(0)
	s_barrier
	v_mfma_f32_16x16x32_bf16 v[8:11], v[134:137], v[166:169], v[8:11]
	v_mfma_f32_16x16x32_bf16 v[12:15], v[142:145], v[166:169], v[12:15]
	v_mfma_f32_16x16x32_bf16 v[28:31], v[134:137], v[190:193], v[28:31]
	v_mfma_f32_16x16x32_bf16 v[32:35], v[142:145], v[190:193], v[32:35]
	v_mfma_f32_16x16x32_bf16 v[36:39], v[134:137], v[198:201], v[36:39]
	v_mfma_f32_16x16x32_bf16 v[44:47], v[142:145], v[198:201], v[44:47]
	v_mfma_f32_16x16x32_bf16 v[80:83], v[134:137], v[206:209], v[80:83]
	v_mfma_f32_16x16x32_bf16 v[88:91], v[142:145], v[206:209], v[88:91]
	v_mfma_f32_16x16x32_bf16 v[8:11], v[138:141], v[186:189], v[8:11]
	v_mfma_f32_16x16x32_bf16 v[12:15], v[146:149], v[186:189], v[12:15]
	v_mfma_f32_16x16x32_bf16 v[28:31], v[138:141], v[194:197], v[28:31]
	v_mfma_f32_16x16x32_bf16 v[32:35], v[146:149], v[194:197], v[32:35]
	v_mfma_f32_16x16x32_bf16 v[36:39], v[138:141], v[202:205], v[36:39]
	v_mfma_f32_16x16x32_bf16 v[44:47], v[146:149], v[202:205], v[44:47]
	v_mfma_f32_16x16x32_bf16 v[80:83], v[138:141], v[210:213], v[80:83]
	v_mfma_f32_16x16x32_bf16 v[88:91], v[146:149], v[210:213], v[88:91]
	v_mfma_f32_16x16x32_bf16 v[0:3], v[150:153], v[166:169], v[0:3]
	v_mfma_f32_16x16x32_bf16 v[4:7], v[158:161], v[166:169], v[4:7]
	v_mfma_f32_16x16x32_bf16 v[20:23], v[150:153], v[190:193], v[20:23]
	v_mfma_f32_16x16x32_bf16 v[24:27], v[158:161], v[190:193], v[24:27]
	v_mfma_f32_16x16x32_bf16 v[40:43], v[150:153], v[198:201], v[40:43]
	v_mfma_f32_16x16x32_bf16 v[48:51], v[158:161], v[198:201], v[48:51]
	v_mfma_f32_16x16x32_bf16 v[60:63], v[150:153], v[206:209], v[60:63]
	v_mfma_f32_16x16x32_bf16 v[64:67], v[158:161], v[206:209], v[64:67]
	v_mfma_f32_16x16x32_bf16 v[0:3], v[154:157], v[186:189], v[0:3]
	v_mfma_f32_16x16x32_bf16 v[4:7], v[162:165], v[186:189], v[4:7]
	v_mfma_f32_16x16x32_bf16 v[20:23], v[154:157], v[194:197], v[20:23]
	v_mfma_f32_16x16x32_bf16 v[24:27], v[162:165], v[194:197], v[24:27]
	v_mfma_f32_16x16x32_bf16 v[40:43], v[154:157], v[202:205], v[40:43]
	v_mfma_f32_16x16x32_bf16 v[48:51], v[162:165], v[202:205], v[48:51]
	v_mfma_f32_16x16x32_bf16 v[60:63], v[154:157], v[210:213], v[60:63]
	v_mfma_f32_16x16x32_bf16 v[64:67], v[162:165], v[210:213], v[64:67]
	s_barrier
	s_add_i32 s2, s5, s17
	v_lshl_add_u64 v[170:171], v[170:171], 0, s[6:7]
	s_mov_b32 m0, s2
	ds_read_b128 v[166:169], v240 offset:49152
	ds_read_b128 v[186:189], v240 offset:50176
	ds_read_b128 v[190:193], v240 offset:51200
	ds_read_b128 v[194:197], v240 offset:52224
	ds_read_b128 v[198:201], v240 offset:53248
	ds_read_b128 v[202:205], v240 offset:54272
	ds_read_b128 v[206:209], v240 offset:55296
	ds_read_b128 v[210:213], v240 offset:56320
	global_load_lds_dwordx4 v[170:171], off
	v_lshl_add_u64 v[170:171], v[214:215], 0, s[6:7]
	s_add_i32 m0, s2, 0x2000
	s_add_i32 s2, s33, s17
	global_load_lds_dwordx4 v[170:171], off
	v_lshl_add_u64 v[170:171], v[216:217], 0, s[6:7]
	s_mov_b32 m0, s2
	s_nop 0
	global_load_lds_dwordx4 v[170:171], off
	v_lshl_add_u64 v[170:171], v[224:225], 0, s[6:7]
	s_add_i32 m0, s2, 0x2000
	s_nop 0
	global_load_lds_dwordx4 v[170:171], off
	v_lshl_add_u64 v[170:171], v[226:227], 0, s[6:7]
	s_mov_b32 m0, s63
	s_nop 0
	global_load_lds_dwordx4 v[170:171], off
	v_lshl_add_u64 v[170:171], v[242:243], 0, s[6:7]
	s_mov_b32 m0, s20
	s_nop 0
	global_load_lds_dwordx4 v[170:171], off
	s_waitcnt vmcnt(8)
	s_waitcnt lgkmcnt(0)
	s_barrier
	v_mfma_f32_16x16x32_bf16 v[68:71], v[134:137], v[166:169], v[68:71]
	v_mfma_f32_16x16x32_bf16 v[72:75], v[142:145], v[166:169], v[72:75]
	v_mfma_f32_16x16x32_bf16 v[92:95], v[134:137], v[190:193], v[92:95]
	v_mfma_f32_16x16x32_bf16 v[96:99], v[142:145], v[190:193], v[96:99]
	v_mfma_f32_16x16x32_bf16 v[108:111], v[134:137], v[198:201], v[108:111]
	v_mfma_f32_16x16x32_bf16 v[112:115], v[142:145], v[198:201], v[112:115]
	v_mfma_f32_16x16x32_bf16 v[124:127], v[134:137], v[206:209], v[124:127]
	v_mfma_f32_16x16x32_bf16 v[128:131], v[142:145], v[206:209], v[128:131]
	v_mfma_f32_16x16x32_bf16 v[68:71], v[138:141], v[186:189], v[68:71]
	v_mfma_f32_16x16x32_bf16 v[72:75], v[146:149], v[186:189], v[72:75]
	v_mfma_f32_16x16x32_bf16 v[92:95], v[138:141], v[194:197], v[92:95]
	v_mfma_f32_16x16x32_bf16 v[96:99], v[146:149], v[194:197], v[96:99]
	v_mfma_f32_16x16x32_bf16 v[108:111], v[138:141], v[202:205], v[108:111]
	v_mfma_f32_16x16x32_bf16 v[112:115], v[146:149], v[202:205], v[112:115]
	v_mfma_f32_16x16x32_bf16 v[124:127], v[138:141], v[210:213], v[124:127]
	v_mfma_f32_16x16x32_bf16 v[128:131], v[146:149], v[210:213], v[128:131]
	v_mfma_f32_16x16x32_bf16 v[52:55], v[150:153], v[166:169], v[52:55]
	v_mfma_f32_16x16x32_bf16 v[56:59], v[158:161], v[166:169], v[56:59]
	v_mfma_f32_16x16x32_bf16 v[76:79], v[150:153], v[190:193], v[76:79]
	v_mfma_f32_16x16x32_bf16 v[84:87], v[158:161], v[190:193], v[84:87]
	v_mfma_f32_16x16x32_bf16 v[100:103], v[150:153], v[198:201], v[100:103]
	v_mfma_f32_16x16x32_bf16 v[104:107], v[158:161], v[198:201], v[104:107]
	v_mfma_f32_16x16x32_bf16 v[116:119], v[150:153], v[206:209], v[116:119]
	v_mfma_f32_16x16x32_bf16 v[120:123], v[158:161], v[206:209], v[120:123]
	v_mfma_f32_16x16x32_bf16 v[52:55], v[154:157], v[186:189], v[52:55]
	v_mfma_f32_16x16x32_bf16 v[56:59], v[162:165], v[186:189], v[56:59]
	v_mfma_f32_16x16x32_bf16 v[76:79], v[154:157], v[194:197], v[76:79]
	v_mfma_f32_16x16x32_bf16 v[84:87], v[162:165], v[194:197], v[84:87]
	v_mfma_f32_16x16x32_bf16 v[100:103], v[154:157], v[202:205], v[100:103]
	v_mfma_f32_16x16x32_bf16 v[104:107], v[162:165], v[202:205], v[104:107]
	v_mfma_f32_16x16x32_bf16 v[116:119], v[154:157], v[210:213], v[116:119]
	v_mfma_f32_16x16x32_bf16 v[120:123], v[162:165], v[210:213], v[120:123]
	s_barrier
	s_add_u32 s0, s0, 0x100
	s_addc_u32 s1, s1, 0
	v_lshl_add_u64 v[132:133], v[132:133], 0, s[8:9]
	v_lshl_add_u64 v[18:19], v[18:19], 0, s[8:9]
	s_cmp_ge_u32 s4, s62
	s_mov_b32 s2, s4
	s_cbranch_scc0 .LBB0_344
	s_setprio 0
	v_readlane_b32 s0, v253, 40
	v_readlane_b32 s1, v253, 41
	s_and_b64 vcc, exec, s[0:1]
	s_cbranch_vccz .LBB0_347
	s_barrier
